# attention phase: one static s_setprio 1 for waves 4..7 (the later-dispatched half), set once at phase entry
# speedup vs baseline: 1.0001x; 1.0001x over previous
.LBB0_471:
	s_or_b64 exec, exec, s[0:1]
	v_readlane_b32 s0, v254, 41
	v_readlane_b32 s1, v254, 42
	s_andn2_b64 vcc, exec, s[0:1]
	s_waitcnt lgkmcnt(0)
	s_barrier
	v_readfirstlane_b32 s98, v234
	s_nop 3
	s_bfe_u32 s98, s98, 0x10008
	s_cmp_lg_u32 s98, 1
	s_cbranch_scc1 .Laprio_skip
	s_setprio 1
.Laprio_skip:
	v_readlane_b32 s100, v253, 31
	v_readlane_b32 s101, v253, 32
	s_cmp_gt_u32 s96, 2
	s_cselect_b32 s98, 0x100, 0
	v_and_b32_e32 v214, 63, v234
	v_lshl_add_u32 v214, v214, 2, s98
	s_nop 4
	global_load_dword v215, v214, s[100:101]
	v_readlane_b32 s100, v253, 33
	v_readlane_b32 s101, v253, 34
	s_nop 4
	global_load_dword v216, v214, s[100:101]
	s_waitcnt vmcnt(0)
	v_and_b32_e32 v215, 0x7fffffff, v215
	v_and_b32_e32 v216, 0x7fffffff, v216
	v_max_f32_e32 v215, v215, v216
	s_nop 1
	v_max_f32_dpp v215, v215, v215 quad_perm:[1,0,3,2] row_mask:0xf bank_mask:0xf bound_ctrl:1
	s_nop 1
	v_max_f32_dpp v215, v215, v215 quad_perm:[2,3,0,1] row_mask:0xf bank_mask:0xf bound_ctrl:1
	s_nop 1
	v_max_f32_dpp v215, v215, v215 row_half_mirror row_mask:0xf bank_mask:0xf bound_ctrl:1
	s_nop 1
	v_max_f32_dpp v215, v215, v215 row_mirror row_mask:0xf bank_mask:0xf bound_ctrl:1
	v_mov_b32_e32 v216, v215
	s_nop 1
	v_permlane16_swap_b32_e32 v215, v216
	v_max_f32_e32 v215, v215, v216
	v_mov_b32_e32 v216, v215
	s_nop 1
	v_permlane32_swap_b32_e32 v215, v216
	v_max_f32_e32 v215, v215, v216
	v_mul_f32_e32 v215, v215, v215
	s_nop 1
	v_readfirstlane_b32 s98, v215
	s_nop 3
	s_cmp_lt_u32 s98, 0x40800000
	s_cselect_b32 s99, 1, 0
	s_cbranch_vccnz .LBB0_474
	v_mov_b32_e32 v0, v234
	s_movk_i32 s0, 0x100
	v_ashrrev_i32_e32 v4, 8, v0
	v_cmp_gt_u32_e32 vcc, s0, v0
	v_ashrrev_i32_e32 v5, 31, v4
	v_readlane_b32 s0, v254, 43
	v_lshlrev_b64 v[2:3], 11, v[4:5]
	v_mov_b32_e32 v6, 2
	v_lshlrev_b64 v[4:5], 10, v[4:5]
	v_readlane_b32 s1, v254, 44
	v_lshl_add_u64 v[2:3], s[28:29], 0, v[2:3]
	v_lshlrev_b32_sdwa v0, v6, v0 dst_sel:DWORD dst_unused:UNUSED_PAD src0_sel:DWORD src1_sel:BYTE_0
	v_lshl_add_u64 v[4:5], s[0:1], 0, v[4:5]
	v_lshl_add_u64 v[2:3], v[2:3], 0, v[0:1]
	v_lshl_add_u64 v[4:5], v[4:5], 0, v[0:1]
	s_mov_b32 s1, 0
	v_mov_b32_e32 v70, 0
	s_movk_i32 s0, 0x67
